# main GQA k-tile loop: all K fragments prefetched before the QK MFMAs, V fragments read during the softmax, PV MFMAs without LDS waits
# speedup vs baseline: 1.0594x; 1.0078x over previous
; template <int D>
; DI void attn_pass(const bfr* __restrict__ P, int b, int tq_wave, int qcol, int kcol, int vcol, int key0, int nkt, char* smem, f32x16 (&o)[2]) {
;     ...
;     __syncthreads();
;     if (kt + 1 < nkt) {
;       const bfr* Pn = Pb + (size_t)(kt + 1) * 64 * PW;
;       { int c = gt, row = c >> 3, kc = c & 7; kreg[0] = *(const u32x4*)(Pn + (size_t)row * PW + kcol + kc * 8); vreg[0] = *(const u32x4*)(Pn + (size_t)row * PW + vcol + kc * 8); }
;     }
;     f32x16 s[2];
; #pragma unroll
;     for (int t2 = 0; t2 < 2; ++t2) {
; #pragma unroll
;       for (int i = 0; i < 16; ++i) s[t2][i] = 0.f;
; #pragma unroll
;       for (int ks = 0; ks < KS; ++ks) {
;         bf16x8 a = *(const bf16x8*)(sK + (t2 * 32 + r) * KP + ks * 16 + h * 8);
;         s[t2] = MFMA32(a, qf[ks], s[t2]);
;       }
;     }
;     float mx = s[0][0];
; #pragma unroll
;     for (int i = 0; i < 16; ++i) { mx = fmaxf(mx, s[0][i]); mx = fmaxf(mx, s[1][i]); }
;     mx = fmaxf(mx, __shfl_xor(mx, 32));
;     float mnew = fmaxf(mrun, mx);
;     float alpha = __builtin_amdgcn_exp2f(mrun - mnew);
;     mrun = mnew;
;     float ps = 0.f;
; #pragma unroll
;     for (int i = 0; i < 16; ++i) {
;       s[0][i] = __builtin_amdgcn_exp2f(s[0][i] - mnew); ps += s[0][i];
;       s[1][i] = __builtin_amdgcn_exp2f(s[1][i] - mnew); ps += s[1][i];
;     }
;     lsum = lsum * alpha + ps;
; #pragma unroll
;     for (int i = 0; i < 16; ++i) { accO[0][i] *= alpha; accO[1][i] *= alpha; }
; #pragma unroll
;     for (int t2 = 0; t2 < 2; ++t2)
; #pragma unroll
;       for (int j = 0; j < 2; ++j) {
;         unsigned pk[4];
; #pragma unroll
;         for (int e = 0; e < 4; ++e) pk[e] = pack2(s[t2][8 * j + 2 * e], s[t2][8 * j + 2 * e + 1]);
;         u32x4 pku = {pk[0], pk[1], pk[2], pk[3]};
;         bf16x8 pf = __builtin_bit_cast(bf16x8, pku);
; #pragma unroll
;         for (int dt = 0; dt < 2; ++dt) {
;           const int vsw = (((dt * 32 + r) >> 3) & 7) << 3;
;           const bfr* vrow = sV + (dt * 32 + r) * 72;
;           s16x4 lo = *(const s16x4*)(vrow + ((t2 * 32 + 16 * j + 4 * h) ^ vsw));
;           s16x4 hi = *(const s16x4*)(vrow + ((t2 * 32 + 16 * j + 4 * h + 8) ^ vsw));
;           bf16x8 vf = __builtin_shufflevector(lo, hi, 0, 1, 2, 3, 4, 5, 6, 7);
;           accO[dt] = MFMA32(vf, pf, accO[dt]);
;         }
;       }
.LBB0_412:
	s_bitcmp1_b32 s8, 0
	s_cselect_b32 s9, 0x4800, 0
	s_add_i32 s9, s9, 0
	v_add3_u32 v32, s9, v115, v90
	v_add_u32_e32 v121, s9, v114
	v_mov_b32_e32 v120, v113
	s_waitcnt vmcnt(1)
	ds_write_b128 v32, v[84:87]
	v_add3_u32 v32, s9, v117, v118
	v_add3_u32 v33, s9, v118, v117
	v_add_u32_e32 v113, v121, v152
	s_waitcnt vmcnt(0)
	ds_write_b16 v32, v80 offset:9216
	ds_write_b16_d16_hi v33, v80 offset:9360
	ds_write_b16 v32, v81 offset:9504
	ds_write_b16_d16_hi v33, v81 offset:9648
	ds_write_b16 v32, v82 offset:9792
	ds_write_b16_d16_hi v33, v82 offset:9936
	ds_write_b16 v32, v83 offset:10080
	ds_write_b16_d16_hi v33, v83 offset:10224
	s_waitcnt lgkmcnt(0)
	s_barrier
	global_load_dwordx4 v[84:87], v[92:93], off
	global_load_dwordx4 v[80:83], v[94:95], off
	ds_read_b128 v[126:129], v113
	ds_read_b128 v[130:133], v113 offset:32
	ds_read_b128 v[134:137], v113 offset:64
	ds_read_b128 v[138:141], v113 offset:96
	ds_read_b128 v[142:145], v113 offset:4608
	ds_read_b128 v[146:149], v113 offset:4640
	ds_read_b128 v[154:157], v113 offset:4672
	ds_read_b128 v[158:161], v113 offset:4704
	v_mov_b32_e32 v96, v119
	s_waitcnt lgkmcnt(7)
	v_mfma_f32_32x32x16_bf16 v[32:47], v[126:129], v[76:79], 0
	s_add_i32 s8, s8, 1
	s_waitcnt lgkmcnt(6)
	v_mfma_f32_32x32x16_bf16 v[32:47], v[130:133], v[72:75], v[32:47]
	v_lshl_add_u64 v[92:93], v[92:93], 0, s[10:11]
	s_waitcnt lgkmcnt(5)
	v_mfma_f32_32x32x16_bf16 v[32:47], v[134:137], v[68:71], v[32:47]
	v_lshl_add_u64 v[94:95], v[94:95], 0, s[10:11]
	s_waitcnt lgkmcnt(4)
	v_mfma_f32_32x32x16_bf16 v[32:47], v[138:141], v[64:67], v[32:47]
	s_cmp_lg_u32 s8, 35
	s_waitcnt lgkmcnt(3)
	v_mfma_f32_32x32x16_bf16 v[48:63], v[142:145], v[76:79], 0
	s_waitcnt lgkmcnt(2)
	v_mfma_f32_32x32x16_bf16 v[48:63], v[146:149], v[72:75], v[48:63]
	s_waitcnt lgkmcnt(1)
	v_mfma_f32_32x32x16_bf16 v[48:63], v[154:157], v[68:71], v[48:63]
	s_waitcnt lgkmcnt(0)
	v_mfma_f32_32x32x16_bf16 v[48:63], v[158:161], v[64:67], v[48:63]
	v_add_u32_e32 v180, s9, v116
	v_lshl_add_u32 v164, v112, 1, v121
	v_lshl_add_u32 v165, v111, 1, v121
	v_lshl_add_u32 v166, v110, 1, v180
	v_lshl_add_u32 v167, v109, 1, v180
	v_lshl_add_u32 v168, v108, 1, v121
	v_lshl_add_u32 v169, v107, 1, v121
	v_lshl_add_u32 v170, v106, 1, v180
	v_lshl_add_u32 v171, v105, 1, v180
	v_lshl_add_u32 v172, v104, 1, v121
	v_lshl_add_u32 v173, v103, 1, v180
	v_lshl_add_u32 v174, v102, 1, v180
	v_lshl_add_u32 v175, v100, 1, v121
	v_lshl_add_u32 v176, v101, 1, v121
	v_lshl_add_u32 v177, v99, 1, v180
	v_lshl_add_u32 v178, v98, 1, v180
	v_max_f32_e32 v119, v32, v32
	v_max_f32_e32 v113, v48, v48
	v_max_f32_e32 v113, v119, v113
	v_max3_f32 v113, v113, v33, v49
	v_max3_f32 v113, v113, v34, v50
	v_max3_f32 v113, v113, v35, v51
	v_max3_f32 v113, v113, v36, v52
	v_max3_f32 v113, v113, v37, v53
	v_max3_f32 v113, v113, v38, v54
	v_max3_f32 v113, v113, v39, v55
	v_max3_f32 v113, v113, v40, v56
	v_max3_f32 v113, v113, v41, v57
	v_max3_f32 v113, v113, v42, v58
	v_max3_f32 v113, v113, v43, v59
	v_max3_f32 v113, v113, v44, v60
	v_max3_f32 v113, v113, v45, v61
	v_max3_f32 v113, v113, v46, v62
	v_max3_f32 v113, v113, v47, v63
	ds_bpermute_b32 v119, v91, v113
	s_waitcnt lgkmcnt(0)
	ds_read_b64 v[126:127], v164 offset:9216
	ds_read_b64 v[128:129], v165 offset:9216
	ds_read_b64 v[130:131], v166 offset:9216
	ds_read_b64 v[132:133], v167 offset:9216
	ds_read_b64 v[134:135], v168 offset:9216
	ds_read_b64 v[136:137], v169 offset:9216
	ds_read_b64 v[138:139], v170 offset:9216
	ds_read_b64 v[140:141], v171 offset:9216
	v_max3_f32 v119, v96, v113, v119
	v_sub_f32_e32 v32, v32, v119
	v_sub_f32_e32 v38, v38, v119
	v_exp_f32_e32 v32, v32
	v_sub_f32_e32 v48, v48, v119
	v_sub_f32_e32 v36, v36, v119
	v_exp_f32_e32 v124, v38
	v_sub_f32_e32 v38, v54, v119
	v_exp_f32_e32 v48, v48
	v_sub_f32_e32 v33, v33, v119
	v_exp_f32_e32 v122, v36
	v_sub_f32_e32 v36, v52, v119
	v_exp_f32_e32 v52, v38
	v_sub_f32_e32 v38, v39, v119
	v_exp_f32_e32 v33, v33
	v_sub_f32_e32 v49, v49, v119
	v_sub_f32_e32 v37, v37, v119
	v_exp_f32_e32 v125, v38
	v_sub_f32_e32 v38, v55, v119
	v_exp_f32_e32 v49, v49
	v_sub_f32_e32 v34, v34, v119
	v_exp_f32_e32 v123, v37
	v_sub_f32_e32 v37, v53, v119
	v_exp_f32_e32 v53, v38
	v_sub_f32_e32 v38, v40, v119
	v_sub_f32_e32 v40, v42, v119
	v_sub_f32_e32 v42, v44, v119
	v_exp_f32_e32 v34, v34
	v_sub_f32_e32 v50, v50, v119
	v_exp_f32_e32 v54, v38
	v_sub_f32_e32 v38, v56, v119
	v_exp_f32_e32 v56, v40
	v_sub_f32_e32 v40, v58, v119
	v_exp_f32_e32 v58, v42
	v_sub_f32_e32 v42, v60, v119
	s_waitcnt lgkmcnt(4)
; #define MFMA32(a, b, c) __builtin_amdgcn_mfma_f32_32x32x16_bf16((a), (b), (c), 0, 0, 0)
; DI unsigned pack2(float a, float b) { unsigned r; asm volatile("v_cvt_pk_bf16_f32 %0, %1, %2" : "=v"(r) : "v"(a), "v"(b)); return r; }
; template <int D>
; DI void attn_pass(const bfr* __restrict__ P, int b, int tq_wave, int qcol, int kcol, int vcol, int key0, int nkt, char* smem, f32x16 (&o)[2]) {
;     ...
;     float mx = s[0][0];
; #pragma unroll
;     for (int i = 0; i < 16; ++i) { mx = fmaxf(mx, s[0][i]); mx = fmaxf(mx, s[1][i]); }
;     mx = fmaxf(mx, __shfl_xor(mx, 32));
;     float mnew = fmaxf(mrun, mx);
;     float alpha = __builtin_amdgcn_exp2f(mrun - mnew);
;     mrun = mnew;
;     float ps = 0.f;
; #pragma unroll
;     for (int i = 0; i < 16; ++i) {
;       s[0][i] = __builtin_amdgcn_exp2f(s[0][i] - mnew); ps += s[0][i];
;       s[1][i] = __builtin_amdgcn_exp2f(s[1][i] - mnew); ps += s[1][i];
;     }
;     lsum = lsum * alpha + ps;
; #pragma unroll
;     for (int i = 0; i < 16; ++i) { accO[0][i] *= alpha; accO[1][i] *= alpha; }
; #pragma unroll
;     for (int t2 = 0; t2 < 2; ++t2)
; #pragma unroll
;       for (int j = 0; j < 2; ++j) {
;         unsigned pk[4];
; #pragma unroll
;         for (int e = 0; e < 4; ++e) pk[e] = pack2(s[t2][8 * j + 2 * e], s[t2][8 * j + 2 * e + 1]);
;         u32x4 pku = {pk[0], pk[1], pk[2], pk[3]};
;         bf16x8 pf = __builtin_bit_cast(bf16x8, pku);
; #pragma unroll
;         for (int dt = 0; dt < 2; ++dt) {
;           const int vsw = (((dt * 32 + r) >> 3) & 7) << 3;
;           const bfr* vrow = sV + (dt * 32 + r) * 72;
;           s16x4 lo = *(const s16x4*)(vrow + ((t2 * 32 + 16 * j + 4 * h) ^ vsw));
;           s16x4 hi = *(const s16x4*)(vrow + ((t2 * 32 + 16 * j + 4 * h + 8) ^ vsw));
;           bf16x8 vf = __builtin_shufflevector(lo, hi, 0, 1, 2, 3, 4, 5, 6, 7);
;           accO[dt] = MFMA32(vf, pf, accO[dt]);
;         }
;       }
	ds_read_b64 v[142:143], v164 offset:9280
	ds_read_b64 v[144:145], v172 offset:9216
	ds_read_b64 v[146:147], v173 offset:9216
	ds_read_b64 v[148:149], v174 offset:9216
	ds_read_b64 v[154:155], v175 offset:9216
	ds_read_b64 v[156:157], v176 offset:9216
	ds_read_b64 v[158:159], v177 offset:9216
	ds_read_b64 v[160:161], v178 offset:9216
	v_add_f32_e32 v60, 0, v32
	v_exp_f32_e32 v50, v50
	v_sub_f32_e32 v35, v35, v119
	v_add_f32_e32 v60, v48, v60
	v_exp_f32_e32 v35, v35
	v_sub_f32_e32 v51, v51, v119
	v_add_f32_e32 v60, v33, v60
	v_exp_f32_e32 v51, v51
	v_add_f32_e32 v60, v49, v60
	v_add_f32_e32 v60, v34, v60
	v_exp_f32_e32 v36, v36
	v_add_f32_e32 v60, v50, v60
	v_add_f32_e32 v60, v35, v60
	v_exp_f32_e32 v37, v37
	v_add_f32_e32 v60, v51, v60
	v_add_f32_e32 v60, v122, v60
	v_add_f32_e32 v60, v36, v60
	v_add_f32_e32 v60, v123, v60
	v_add_f32_e32 v60, v37, v60
	v_add_f32_e32 v60, v124, v60
	v_exp_f32_e32 v38, v38
	v_sub_f32_e32 v39, v41, v119
	v_add_f32_e32 v60, v52, v60
	v_exp_f32_e32 v55, v39
	v_sub_f32_e32 v39, v57, v119
	v_add_f32_e32 v60, v125, v60
	v_exp_f32_e32 v39, v39
	v_add_f32_e32 v60, v53, v60
	v_add_f32_e32 v60, v54, v60
	v_exp_f32_e32 v40, v40
	v_sub_f32_e32 v41, v43, v119
	v_add_f32_e32 v60, v38, v60
	v_exp_f32_e32 v57, v41
	v_sub_f32_e32 v41, v59, v119
	v_add_f32_e32 v60, v55, v60
	v_exp_f32_e32 v41, v41
	v_add_f32_e32 v60, v39, v60
	v_add_f32_e32 v60, v56, v60
	v_exp_f32_e32 v42, v42
	v_sub_f32_e32 v43, v45, v119
	v_add_f32_e32 v60, v40, v60
	v_exp_f32_e32 v59, v43
	v_sub_f32_e32 v43, v61, v119
	v_add_f32_e32 v60, v57, v60
	v_exp_f32_e32 v43, v43
	v_sub_f32_e32 v44, v46, v119
	v_add_f32_e32 v60, v41, v60
	v_exp_f32_e32 v46, v44
	v_sub_f32_e32 v44, v62, v119
	v_add_f32_e32 v60, v58, v60
	v_exp_f32_e32 v44, v44
	v_sub_f32_e32 v45, v47, v119
	v_add_f32_e32 v60, v42, v60
	v_exp_f32_e32 v47, v45
	v_sub_f32_e32 v45, v63, v119
	v_add_f32_e32 v60, v59, v60
	v_exp_f32_e32 v45, v45
	v_add_f32_e32 v60, v43, v60
	v_add_f32_e32 v60, v46, v60
	v_add_f32_e32 v60, v44, v60
	v_add_f32_e32 v60, v47, v60
	v_add_f32_e32 v113, v45, v60
	v_cvt_pk_bf16_f32 v32, v32, v33
	v_cvt_pk_bf16_f32 v33, v34, v35
	v_cvt_pk_bf16_f32 v34, v122, v123
	v_cvt_pk_bf16_f32 v35, v124, v125
	v_sub_f32_e32 v96, v96, v119
	v_exp_f32_e32 v96, v96
	s_nop 1
	v_pk_mul_f32 v[30:31], v[30:31], v[96:97] op_sel_hi:[1,0]
	v_pk_mul_f32 v[28:29], v[28:29], v[96:97] op_sel_hi:[1,0]
	v_pk_mul_f32 v[26:27], v[26:27], v[96:97] op_sel_hi:[1,0]
	v_pk_mul_f32 v[24:25], v[24:25], v[96:97] op_sel_hi:[1,0]
	v_pk_mul_f32 v[22:23], v[22:23], v[96:97] op_sel_hi:[1,0]
	v_pk_mul_f32 v[20:21], v[20:21], v[96:97] op_sel_hi:[1,0]
	v_pk_mul_f32 v[18:19], v[18:19], v[96:97] op_sel_hi:[1,0]
	v_pk_mul_f32 v[16:17], v[16:17], v[96:97] op_sel_hi:[1,0]
	v_pk_mul_f32 v[14:15], v[14:15], v[96:97] op_sel_hi:[1,0]
	v_pk_mul_f32 v[12:13], v[12:13], v[96:97] op_sel_hi:[1,0]
	s_waitcnt lgkmcnt(0)
	v_mfma_f32_32x32x16_bf16 v[16:31], v[126:129], v[32:35], v[16:31]
	v_mul_f32_e64 v10, v10, v96
	v_mul_f32_e64 v11, v11, v96
	v_pk_mul_f32 v[8:9], v[8:9], v[96:97] op_sel_hi:[1,0]
	v_pk_mul_f32 v[6:7], v[6:7], v[96:97] op_sel_hi:[1,0]
	v_pk_mul_f32 v[4:5], v[4:5], v[96:97] op_sel_hi:[1,0]
	v_pk_mul_f32 v[2:3], v[2:3], v[96:97] op_sel_hi:[1,0]
	v_pk_mul_f32 v[0:1], v[0:1], v[96:97] op_sel_hi:[1,0]
	v_fmac_f32_e32 v113, v120, v96
	s_nop 1
	v_mfma_f32_32x32x16_bf16 v[0:15], v[130:133], v[32:35], v[0:15]
	v_cvt_pk_bf16_f32 v32, v54, v55
	v_cvt_pk_bf16_f32 v33, v56, v57
	v_cvt_pk_bf16_f32 v34, v58, v59
	v_cvt_pk_bf16_f32 v35, v46, v47
	s_nop 1
	v_mfma_f32_32x32x16_bf16 v[16:31], v[134:137], v[32:35], v[16:31]
	s_nop 1
	v_mfma_f32_32x32x16_bf16 v[0:15], v[138:141], v[32:35], v[0:15]
	v_cvt_pk_bf16_f32 v32, v48, v49
	v_cvt_pk_bf16_f32 v33, v50, v51
	v_cvt_pk_bf16_f32 v34, v36, v37
	v_cvt_pk_bf16_f32 v35, v52, v53
	s_nop 1
	v_mfma_f32_32x32x16_bf16 v[16:31], v[142:145], v[32:35], v[16:31]
	s_nop 1
	v_mfma_f32_32x32x16_bf16 v[0:15], v[146:149], v[32:35], v[0:15]
	v_cvt_pk_bf16_f32 v32, v38, v39
	v_cvt_pk_bf16_f32 v33, v40, v41
	v_cvt_pk_bf16_f32 v34, v42, v43
	v_cvt_pk_bf16_f32 v35, v44, v45
	s_nop 1
	v_mfma_f32_32x32x16_bf16 v[16:31], v[154:157], v[32:35], v[16:31]
	s_nop 1
	v_mfma_f32_32x32x16_bf16 v[0:15], v[158:161], v[32:35], v[0:15]
	s_cbranch_scc1 .LBB0_412
	v_add3_u32 v32, 0, v115, v90
	s_waitcnt vmcnt(1)
	ds_write_b128 v32, v[84:87] offset:18432
	v_add3_u32 v32, 0, v117, v118
	v_add3_u32 v33, 0, v118, v117
	s_waitcnt vmcnt(0)
	ds_write_b16 v32, v80 offset:27648
	ds_write_b16_d16_hi v33, v80 offset:27792
	ds_write_b16 v32, v81 offset:27936
	ds_write_b16_d16_hi v33, v81 offset:28080
	ds_write_b16 v32, v82 offset:28224
	ds_write_b16_d16_hi v33, v82 offset:28368
	ds_write_b16 v32, v83 offset:28512
	ds_write_b16_d16_hi v33, v83 offset:28656
	v_add_u32_e32 v80, 0, v114
	v_add_u32_e32 v81, v80, v152
	s_waitcnt lgkmcnt(0)
	s_barrier
; #define MFMA32(a, b, c) __builtin_amdgcn_mfma_f32_32x32x16_bf16((a), (b), (c), 0, 0, 0)
; DI unsigned pack2(float a, float b) { unsigned r; asm volatile("v_cvt_pk_bf16_f32 %0, %1, %2" : "=v"(r) : "v"(a), "v"(b)); return r; }
; template <int D>
; DI void attn_pass(const bfr* __restrict__ P, int b, int tq_wave, int qcol, int kcol, int vcol, int key0, int nkt, char* smem, f32x16 (&o)[2]) {
;     ...
;     f32x16 s[2];
; #pragma unroll
;     for (int t2 = 0; t2 < 2; ++t2) {
; #pragma unroll
;       for (int i = 0; i < 16; ++i) s[t2][i] = 0.f;
; #pragma unroll
;       for (int ks = 0; ks < KS; ++ks) {
;         bf16x8 a = *(const bf16x8*)(sK + (t2 * 32 + r) * KP + ks * 16 + h * 8);
;         s[t2] = MFMA32(a, qf[ks], s[t2]);
;       }
;     }
;     float mx = s[0][0];
; #pragma unroll
;     for (int i = 0; i < 16; ++i) { mx = fmaxf(mx, s[0][i]); mx = fmaxf(mx, s[1][i]); }
;     mx = fmaxf(mx, __shfl_xor(mx, 32));
;     float mnew = fmaxf(mrun, mx);
;     float alpha = __builtin_amdgcn_exp2f(mrun - mnew);
;     mrun = mnew;
;     float ps = 0.f;
; #pragma unroll
;     for (int i = 0; i < 16; ++i) {
;       s[0][i] = __builtin_amdgcn_exp2f(s[0][i] - mnew); ps += s[0][i];
;       s[1][i] = __builtin_amdgcn_exp2f(s[1][i] - mnew); ps += s[1][i];
;     }
;     lsum = lsum * alpha + ps;
; #pragma unroll
;     for (int i = 0; i < 16; ++i) { accO[0][i] *= alpha; accO[1][i] *= alpha; }
; #pragma unroll
;     for (int t2 = 0; t2 < 2; ++t2)
; #pragma unroll
;       for (int j = 0; j < 2; ++j) {
;         unsigned pk[4];
; #pragma unroll
;         for (int e = 0; e < 4; ++e) pk[e] = pack2(s[t2][8 * j + 2 * e], s[t2][8 * j + 2 * e + 1]);
;         u32x4 pku = {pk[0], pk[1], pk[2], pk[3]};
;         bf16x8 pf = __builtin_bit_cast(bf16x8, pku);
; #pragma unroll
;         for (int dt = 0; dt < 2; ++dt) {
;           const int vsw = (((dt * 32 + r) >> 3) & 7) << 3;
;           const bfr* vrow = sV + (dt * 32 + r) * 72;
;           s16x4 lo = *(const s16x4*)(vrow + ((t2 * 32 + 16 * j + 4 * h) ^ vsw));
;           s16x4 hi = *(const s16x4*)(vrow + ((t2 * 32 + 16 * j + 4 * h + 8) ^ vsw));
;           bf16x8 vf = __builtin_shufflevector(lo, hi, 0, 1, 2, 3, 4, 5, 6, 7);
;           accO[dt] = MFMA32(vf, pf, accO[dt]);
;         }
;       }
	ds_read_b128 v[32:35], v81 offset:18432
	ds_read_b128 v[48:51], v81 offset:18464
	s_waitcnt lgkmcnt(1)
	v_mfma_f32_32x32x16_bf16 v[32:47], v[32:35], v[76:79], 0
	v_lshlrev_b32_e32 v152, 1, v88
	s_waitcnt lgkmcnt(0)
	v_mfma_f32_32x32x16_bf16 v[32:47], v[48:51], v[72:75], v[32:47]
	ds_read_b128 v[48:51], v81 offset:18496
	s_waitcnt lgkmcnt(0)
	v_mfma_f32_32x32x16_bf16 v[32:47], v[48:51], v[68:71], v[32:47]
	ds_read_b128 v[48:51], v81 offset:18528
	s_waitcnt lgkmcnt(0)
	v_mfma_f32_32x32x16_bf16 v[32:47], v[48:51], v[64:67], v[32:47]
	ds_read_b128 v[48:51], v81 offset:23040
	s_waitcnt lgkmcnt(0)
	v_mfma_f32_32x32x16_bf16 v[48:63], v[48:51], v[76:79], 0
	ds_read_b128 v[76:79], v81 offset:23072
	s_waitcnt lgkmcnt(0)
	v_mfma_f32_32x32x16_bf16 v[48:63], v[76:79], v[72:75], v[48:63]
	ds_read_b128 v[72:75], v81 offset:23104
	s_waitcnt lgkmcnt(0)
	v_mfma_f32_32x32x16_bf16 v[48:63], v[72:75], v[68:71], v[48:63]
	ds_read_b128 v[68:71], v81 offset:23136
	s_waitcnt lgkmcnt(0)
	v_mfma_f32_32x32x16_bf16 v[48:63], v[68:71], v[64:67], v[48:63]
	v_max_f32_e32 v65, v32, v32
	v_lshl_add_u32 v66, v112, 1, v80
	v_add_u32_e32 v67, 0x1200, v80
	s_nop 8
	v_max_f32_e32 v64, v48, v48
	v_max_f32_e32 v64, v65, v64
	v_max3_f32 v64, v64, v33, v49
	v_max3_f32 v64, v64, v34, v50
	v_max3_f32 v64, v64, v35, v51
	v_max3_f32 v64, v64, v36, v52
	v_max3_f32 v64, v64, v37, v53
	v_max3_f32 v64, v64, v38, v54
	v_max3_f32 v64, v64, v39, v55
	v_max3_f32 v64, v64, v40, v56
	v_max3_f32 v64, v64, v41, v57
	v_max3_f32 v64, v64, v42, v58
	v_max3_f32 v64, v64, v43, v59
	v_max3_f32 v64, v64, v44, v60
	v_max3_f32 v64, v64, v45, v61
	v_max3_f32 v64, v64, v46, v62
	v_max3_f32 v64, v64, v47, v63
	ds_bpermute_b32 v65, v91, v64
	s_waitcnt lgkmcnt(0)
	v_max3_f32 v65, v119, v64, v65
	v_sub_f32_e32 v64, v119, v65
	v_sub_f32_e32 v32, v32, v65
	v_exp_f32_e32 v64, v64
	v_exp_f32_e32 v32, v32
	v_sub_f32_e32 v48, v48, v65
	v_exp_f32_e32 v48, v48
	v_sub_f32_e32 v33, v33, v65
	v_exp_f32_e32 v33, v33
	v_sub_f32_e32 v49, v49, v65
	v_exp_f32_e32 v49, v49
	v_sub_f32_e32 v34, v34, v65
	v_exp_f32_e32 v34, v34
	v_sub_f32_e32 v50, v50, v65
	v_sub_f32_e32 v35, v35, v65
	v_sub_f32_e32 v51, v51, v65
	v_sub_f32_e32 v36, v36, v65
	v_sub_f32_e32 v52, v52, v65
	v_sub_f32_e32 v37, v37, v65
	v_sub_f32_e32 v53, v53, v65
	v_sub_f32_e32 v38, v38, v65
	v_sub_f32_e32 v54, v54, v65
	v_sub_f32_e32 v39, v39, v65
	v_sub_f32_e32 v55, v55, v65
	v_sub_f32_e32 v40, v40, v65
	v_sub_f32_e32 v56, v56, v65
	v_sub_f32_e32 v41, v41, v65
	v_sub_f32_e32 v57, v57, v65
	v_sub_f32_e32 v42, v42, v65
	v_sub_f32_e32 v58, v58, v65
	v_sub_f32_e32 v43, v43, v65
	v_sub_f32_e32 v59, v59, v65
	v_sub_f32_e32 v44, v44, v65
	v_sub_f32_e32 v60, v60, v65
	v_sub_f32_e32 v45, v45, v65
	v_sub_f32_e32 v61, v61, v65
	v_sub_f32_e32 v46, v46, v65
	v_sub_f32_e32 v62, v62, v65
	v_sub_f32_e32 v47, v47, v65
	v_sub_f32_e32 v63, v63, v65
	v_pk_mul_f32 v[30:31], v[30:31], v[64:65] op_sel_hi:[1,0]
	v_pk_mul_f32 v[28:29], v[28:29], v[64:65] op_sel_hi:[1,0]
	v_pk_mul_f32 v[26:27], v[26:27], v[64:65] op_sel_hi:[1,0]
	v_pk_mul_f32 v[24:25], v[24:25], v[64:65] op_sel_hi:[1,0]
	v_pk_mul_f32 v[22:23], v[22:23], v[64:65] op_sel_hi:[1,0]
	v_pk_mul_f32 v[20:21], v[20:21], v[64:65] op_sel_hi:[1,0]
	v_pk_mul_f32 v[18:19], v[18:19], v[64:65] op_sel_hi:[1,0]
	v_pk_mul_f32 v[16:17], v[16:17], v[64:65] op_sel_hi:[1,0]
	v_pk_mul_f32 v[14:15], v[14:15], v[64:65] op_sel_hi:[1,0]
	v_pk_mul_f32 v[12:13], v[12:13], v[64:65] op_sel_hi:[1,0]
	v_pk_mul_f32 v[10:11], v[10:11], v[64:65] op_sel_hi:[1,0]
	v_pk_mul_f32 v[8:9], v[8:9], v[64:65] op_sel_hi:[1,0]
	v_pk_mul_f32 v[6:7], v[6:7], v[64:65] op_sel_hi:[1,0]
	v_pk_mul_f32 v[4:5], v[4:5], v[64:65] op_sel_hi:[1,0]
	v_pk_mul_f32 v[2:3], v[2:3], v[64:65] op_sel_hi:[1,0]
	v_pk_mul_f32 v[0:1], v[0:1], v[64:65] op_sel_hi:[1,0]
	v_add_f32_e32 v65, 0, v32
	v_exp_f32_e32 v50, v50
	v_add_f32_e32 v65, v48, v65
	v_exp_f32_e32 v35, v35
	v_add_f32_e32 v65, v33, v65
	v_exp_f32_e32 v51, v51
	v_add_f32_e32 v65, v49, v65
	v_exp_f32_e32 v36, v36
	v_add_f32_e32 v65, v34, v65
	v_exp_f32_e32 v52, v52
	v_add_f32_e32 v65, v50, v65
	v_exp_f32_e32 v37, v37
	v_add_f32_e32 v65, v35, v65
	v_exp_f32_e32 v53, v53
	v_add_f32_e32 v65, v51, v65
	v_exp_f32_e32 v38, v38
	v_add_f32_e32 v65, v36, v65
	v_exp_f32_e32 v54, v54
	v_add_f32_e32 v65, v52, v65
	v_exp_f32_e32 v39, v39
	v_add_f32_e32 v65, v37, v65
	v_add_f32_e32 v65, v53, v65
	v_add_f32_e32 v65, v38, v65
	v_add_f32_e32 v65, v54, v65
	v_cvt_pk_bf16_f32 v32, v32, v33
	v_cvt_pk_bf16_f32 v33, v34, v35
	v_cvt_pk_bf16_f32 v34, v36, v37
	v_cvt_pk_bf16_f32 v35, v38, v39
	v_lshl_add_u32 v38, v111, 1, v80
	v_add_f32_e32 v65, v39, v65
	ds_read_b64 v[36:37], v66 offset:27648
	ds_read_b64 v[38:39], v38 offset:27648
	s_waitcnt lgkmcnt(0)
	v_mfma_f32_32x32x16_bf16 v[16:31], v[36:39], v[32:35], v[16:31]
	v_lshl_add_u32 v36, v110, 1, v67
	v_lshl_add_u32 v38, v109, 1, v67
	ds_read_b64 v[36:37], v36 offset:27648
	ds_read_b64 v[38:39], v38 offset:27648
	v_exp_f32_e32 v40, v40
	v_exp_f32_e32 v41, v41
	v_exp_f32_e32 v42, v42
	s_waitcnt lgkmcnt(0)
; #define MFMA32(a, b, c) __builtin_amdgcn_mfma_f32_32x32x16_bf16((a), (b), (c), 0, 0, 0)
; DI unsigned pack2(float a, float b) { unsigned r; asm volatile("v_cvt_pk_bf16_f32 %0, %1, %2" : "=v"(r) : "v"(a), "v"(b)); return r; }
; template <int D>
; DI void attn_pass(const bfr* __restrict__ P, int b, int tq_wave, int qcol, int kcol, int vcol, int key0, int nkt, char* smem, f32x16 (&o)[2]) {
;     ...
;     for (int i = 0; i < 16; ++i) { accO[0][i] *= alpha; accO[1][i] *= alpha; }
; #pragma unroll
;     for (int t2 = 0; t2 < 2; ++t2)
; #pragma unroll
;       for (int j = 0; j < 2; ++j) {
;         unsigned pk[4];
; #pragma unroll
;         for (int e = 0; e < 4; ++e) pk[e] = pack2(s[t2][8 * j + 2 * e], s[t2][8 * j + 2 * e + 1]);
;         u32x4 pku = {pk[0], pk[1], pk[2], pk[3]};
;         bf16x8 pf = __builtin_bit_cast(bf16x8, pku);
; #pragma unroll
;         for (int dt = 0; dt < 2; ++dt) {
;           const int vsw = (((dt * 32 + r) >> 3) & 7) << 3;
;           const bfr* vrow = sV + (dt * 32 + r) * 72;
;           s16x4 lo = *(const s16x4*)(vrow + ((t2 * 32 + 16 * j + 4 * h) ^ vsw));
;           s16x4 hi = *(const s16x4*)(vrow + ((t2 * 32 + 16 * j + 4 * h + 8) ^ vsw));
;           bf16x8 vf = __builtin_shufflevector(lo, hi, 0, 1, 2, 3, 4, 5, 6, 7);
;           accO[dt] = MFMA32(vf, pf, accO[dt]);
;         }
;       }
;   }
;   lsum += __shfl_xor(lsum, 32);
;   float inv = 1.f / lsum;
; #pragma unroll
;   for (int i = 0; i < 16; ++i) { o[0][i] = accO[0][i] * inv; o[1][i] = accO[1][i] * inv; }
; DI void store_o(bfr* O, int m, int colbase, int h, const f32x16 (&o)[2]) {
; #pragma unroll
;   for (int dt = 0; dt < 2; ++dt)
; #pragma unroll
;     for (int g4 = 0; g4 < 4; ++g4) {
;       int dv = dt * 32 + 8 * g4 + 4 * h;
;       uint2 pk; pk.x = pack2(o[dt][4 * g4], o[dt][4 * g4 + 1]); pk.y = pack2(o[dt][4 * g4 + 2], o[dt][4 * g4 + 3]);
;       *(uint2*)(O + (size_t)m * DM + colbase + dv) = pk;
;     }
	v_mfma_f32_32x32x16_bf16 v[0:15], v[36:39], v[32:35], v[0:15]
	v_lshl_add_u32 v36, v108, 1, v80
	v_lshl_add_u32 v38, v107, 1, v80
	v_exp_f32_e32 v43, v43
	v_exp_f32_e32 v44, v44
	v_exp_f32_e32 v45, v45
	v_exp_f32_e32 v46, v46
	v_exp_f32_e32 v47, v47
	v_cvt_pk_bf16_f32 v32, v40, v41
	v_cvt_pk_bf16_f32 v33, v42, v43
	v_cvt_pk_bf16_f32 v34, v44, v45
	v_cvt_pk_bf16_f32 v35, v46, v47
	ds_read_b64 v[36:37], v36 offset:27648
	ds_read_b64 v[38:39], v38 offset:27648
	s_waitcnt lgkmcnt(0)
	v_mfma_f32_32x32x16_bf16 v[16:31], v[36:39], v[32:35], v[16:31]
	v_lshl_add_u32 v36, v106, 1, v67
	v_lshl_add_u32 v38, v105, 1, v67
	ds_read_b64 v[36:37], v36 offset:27648
	ds_read_b64 v[38:39], v38 offset:27648
	v_exp_f32_e32 v55, v55
	v_exp_f32_e32 v56, v56
	v_exp_f32_e32 v57, v57
	s_waitcnt lgkmcnt(0)
	v_mfma_f32_32x32x16_bf16 v[0:15], v[36:39], v[32:35], v[0:15]
	v_lshl_add_u32 v38, v104, 1, v80
	v_cvt_pk_bf16_f32 v32, v48, v49
	v_cvt_pk_bf16_f32 v33, v50, v51
	v_cvt_pk_bf16_f32 v34, v52, v53
	v_cvt_pk_bf16_f32 v35, v54, v55
	ds_read_b64 v[36:37], v66 offset:27712
	ds_read_b64 v[38:39], v38 offset:27648
	s_waitcnt lgkmcnt(0)
	v_mfma_f32_32x32x16_bf16 v[16:31], v[36:39], v[32:35], v[16:31]
	v_lshl_add_u32 v36, v103, 1, v67
	v_lshl_add_u32 v38, v102, 1, v67
	ds_read_b64 v[36:37], v36 offset:27648
	ds_read_b64 v[38:39], v38 offset:27648
	v_exp_f32_e32 v58, v58
	v_exp_f32_e32 v59, v59
	v_exp_f32_e32 v60, v60
	s_waitcnt lgkmcnt(0)
	v_mfma_f32_32x32x16_bf16 v[0:15], v[36:39], v[32:35], v[0:15]
	v_lshl_add_u32 v36, v100, 1, v80
	v_lshl_add_u32 v38, v101, 1, v80
	v_exp_f32_e32 v61, v61
	v_exp_f32_e32 v62, v62
	v_exp_f32_e32 v63, v63
	v_cvt_pk_bf16_f32 v32, v56, v57
	v_cvt_pk_bf16_f32 v33, v58, v59
	v_cvt_pk_bf16_f32 v34, v60, v61
	v_cvt_pk_bf16_f32 v35, v62, v63
	ds_read_b64 v[36:37], v36 offset:27648
	ds_read_b64 v[38:39], v38 offset:27648
	v_add_f32_e32 v65, v55, v65
	v_add_f32_e32 v65, v40, v65
	v_add_f32_e32 v65, v56, v65
	v_add_f32_e32 v65, v41, v65
	v_add_f32_e32 v65, v57, v65
	v_add_f32_e32 v65, v42, v65
	v_add_f32_e32 v65, v58, v65
	v_add_f32_e32 v65, v43, v65
	v_add_f32_e32 v65, v59, v65
	s_waitcnt lgkmcnt(0)
	v_mfma_f32_32x32x16_bf16 v[16:31], v[36:39], v[32:35], v[16:31]
	v_lshl_add_u32 v36, v99, 1, v67
	v_lshl_add_u32 v38, v98, 1, v67
	v_add_f32_e32 v65, v44, v65
	ds_read_b64 v[36:37], v36 offset:27648
	ds_read_b64 v[38:39], v38 offset:27648
	v_add_f32_e32 v65, v60, v65
	v_add_f32_e32 v65, v45, v65
	v_add_f32_e32 v65, v61, v65
	v_add_f32_e32 v65, v46, v65
	v_add_f32_e32 v65, v62, v65
	v_add_f32_e32 v65, v47, v65
	v_add_f32_e32 v65, v63, v65
	v_fmac_f32_e32 v65, v113, v64
	s_waitcnt lgkmcnt(0)
	v_mfma_f32_32x32x16_bf16 v[0:15], v[36:39], v[32:35], v[0:15]
	ds_bpermute_b32 v32, v91, v65
	s_waitcnt lgkmcnt(0)
	v_add_f32_e32 v32, v65, v32
	v_div_scale_f32 v33, s[8:9], v32, v32, 1.0
	v_rcp_f32_e32 v34, v33
	s_load_dwordx4 s[8:11], s[0:1], 0x100
	s_waitcnt lgkmcnt(0)
	s_mov_b64 s[8:9], 0x2b7c700
	v_fma_f32 v35, -v33, v34, 1.0
	v_fmac_f32_e32 v34, v35, v34
	v_div_scale_f32 v35, vcc, 1.0, v32, 1.0
	v_mul_f32_e32 v36, v35, v34
	v_fma_f32 v37, -v33, v36, v35
	v_fmac_f32_e32 v36, v37, v34
	v_fma_f32 v33, -v33, v36, v35
	v_div_fmas_f32 v33, v33, v34, v36
	v_div_fixup_f32 v32, v33, v32, 1.0
	v_mul_f32_e32 v33, v0, v32
	v_and_or_b32 v0, v89, 31, v97
	v_mul_f32_e32 v34, v1, v32
	v_ashrrev_i32_e32 v1, 31, v0
	v_lshlrev_b64 v[0:1], 11, v[0:1]
	v_mul_f32_e32 v37, v4, v32
	v_lshl_add_u64 v[0:1], s[10:11], 0, v[0:1]
	v_lshrrev_b32_e32 v4, 2, v89
	v_lshl_add_u64 v[0:1], v[0:1], 0, v[152:153]
	v_and_b32_e32 v152, 8, v4
	v_lshl_add_u64 v[0:1], v[0:1], 0, v[152:153]
	v_mul_f32_e32 v38, v5, v32
	v_lshl_add_u64 v[4:5], v[0:1], 0, s[8:9]
	s_mov_b32 s8, 0x2b7c000
	v_add_co_u32_e32 v0, vcc, s8, v0
	v_mul_f32_e32 v16, v16, v32
	s_nop 0
	v_addc_co_u32_e32 v1, vcc, 0, v1, vcc
	v_mul_f32_e32 v17, v17, v32
	v_mul_f32_e32 v18, v18, v32
	v_mul_f32_e32 v35, v2, v32
	v_mul_f32_e32 v19, v19, v32
	v_mul_f32_e32 v36, v3, v32
	v_mul_f32_e32 v20, v20, v32
	v_mul_f32_e32 v21, v21, v32
	v_mul_f32_e32 v22, v22, v32
	v_mul_f32_e32 v23, v23, v32
	v_cvt_pk_bf16_f32 v2, v16, v17
	v_cvt_pk_bf16_f32 v3, v18, v19
	global_store_dwordx2 v[0:1], v[2:3], off offset:1792
	v_cvt_pk_bf16_f32 v0, v20, v21
	v_cvt_pk_bf16_f32 v1, v22, v23
	v_mul_f32_e32 v24, v24, v32
	v_mul_f32_e32 v25, v25, v32
	v_mul_f32_e32 v26, v26, v32
	v_mul_f32_e32 v27, v27, v32
	global_store_dwordx2 v[4:5], v[0:1], off offset:16
	v_cvt_pk_bf16_f32 v0, v24, v25
	v_cvt_pk_bf16_f32 v1, v26, v27
	v_mul_f32_e32 v28, v28, v32
	v_mul_f32_e32 v29, v29, v32
	v_mul_f32_e32 v30, v30, v32
	v_mul_f32_e32 v31, v31, v32
	global_store_dwordx2 v[4:5], v[0:1], off offset:32
	v_cvt_pk_bf16_f32 v0, v28, v29
	v_cvt_pk_bf16_f32 v1, v30, v31
	global_store_dwordx2 v[4:5], v[0:1], off offset:48
	v_cvt_pk_bf16_f32 v0, v33, v34
	v_cvt_pk_bf16_f32 v1, v35, v36
	v_mul_f32_e32 v6, v6, v32
	v_mul_f32_e32 v7, v7, v32
	global_store_dwordx2 v[4:5], v[0:1], off offset:64
	v_cvt_pk_bf16_f32 v0, v37, v38
	v_cvt_pk_bf16_f32 v1, v6, v7
	v_mul_f32_e32 v8, v8, v32
	v_mul_f32_e32 v9, v9, v32
	v_mul_f32_e32 v10, v10, v32
	v_mul_f32_e32 v11, v11, v32
	global_store_dwordx2 v[4:5], v[0:1], off offset:80
	v_cvt_pk_bf16_f32 v0, v8, v9
	v_cvt_pk_bf16_f32 v1, v10, v11
	v_mul_f32_e32 v12, v12, v32
	v_mul_f32_e32 v13, v13, v32
	v_mul_f32_e32 v14, v14, v32
	v_mul_f32_e32 v15, v15, v32
	global_store_dwordx2 v[4:5], v[0:1], off offset:96
	v_cvt_pk_bf16_f32 v0, v12, v13
	v_cvt_pk_bf16_f32 v1, v14, v15
	global_store_dwordx2 v[4:5], v[0:1], off offset:112
